# GEMM phase prologues: K-tile 1 loads issued before the first wait/barrier (vmcnt 2 -> 8)
# baseline (speedup 1.0000x reference)
.LBB0_133:
	s_add_u32 s48, s4, 0x28300000
	s_addc_u32 s49, s5, 0
	s_lshl_b32 s50, s8, 6
	s_lshl_b32 s14, s8, 13
	s_lshl_b32 s8, s9, 5
	s_and_b32 s15, s8, 0x60
	s_mov_b64 s[8:9], 0x80
	s_add_i32 m0, s43, 0x18000
	v_lshl_add_u64 v[8:9], v[8:9], 0, s[8:9]
	s_lshl_b32 s16, s15, 7
	s_nop 0
	global_load_lds_dwordx4 v[8:9], off
	v_lshl_add_u64 v[6:7], v[6:7], 0, s[8:9]
	s_add_i32 m0, s43, 0x1a000
	s_add_i32 s51, s43, 0x8000
	s_add_i32 s53, s43, 0xa000
	global_load_lds_dwordx4 v[6:7], off
	v_lshl_add_u64 v[2:3], v[2:3], 0, s[8:9]
	s_mov_b32 m0, s51
	s_add_u32 s12, s24, 0x80080
	global_load_lds_dwordx4 v[2:3], off
	v_lshl_add_u64 v[2:3], v[4:5], 0, s[8:9]
	s_mov_b32 m0, s53
	s_addc_u32 s13, s25, 0
	global_load_lds_dwordx4 v[2:3], off
	s_add_i32 m0, s43, 0x1c000
	v_lshl_add_u64 v[2:3], s[12:13], 0, v[132:133]
	global_load_lds_dwordx4 v[2:3], off
	v_lshl_add_u64 v[2:3], s[12:13], 0, v[136:137]
	s_add_i32 m0, s43, 0x1e000
	v_and_b32_e32 v157, 15, v10
	global_load_lds_dwordx4 v[2:3], off
	v_bfe_u32 v2, v10, 4, 2
	v_lshlrev_b32_e32 v138, 3, v2
	v_lshlrev_b32_e32 v2, 4, v2
	v_lshlrev_b32_e32 v3, 2, v10
	v_lshl_or_b32 v2, v157, 6, v2
	v_and_b32_e32 v3, 32, v3
	v_bitop3_b32 v4, v2, s14, v3 bitop3:0xde
	v_bitop3_b32 v159, v2, s16, v3 bitop3:0xde
	v_and_b32_e32 v3, 64, v151
	v_xor_b32_e32 v2, 16, v151
	v_add_u32_e32 v3, 64, v3
	v_cmp_lt_i32_e32 vcc, v2, v3
	s_waitcnt vmcnt(8)
	s_barrier
	s_waitcnt vmcnt(6)
	s_cmpk_lt_u32 s11, 0x100
	s_sext_i32_i16 s58, s10
	v_cndmask_b32_e32 v2, v151, v2, vcc
	v_lshlrev_b32_e32 v160, 2, v2
	v_xor_b32_e32 v2, 32, v151
	v_cmp_lt_i32_e32 vcc, v2, v3
	s_cselect_b64 s[10:11], -1, 0
	s_add_i32 s55, 0, 0x10000
	v_cndmask_b32_e32 v2, v151, v2, vcc
	v_lshlrev_b32_e32 v161, 2, v2
	v_lshl_add_u64 v[2:3], s[4:5], 0, v[138:139]
	s_mov_b64 s[4:5], 0x8c0000
	v_lshl_add_u64 v[140:141], v[2:3], 0, s[4:5]
	v_lshlrev_b32_e32 v2, 15, v14
	v_and_b32_e32 v2, 0xffff0000, v2
	v_lshl_add_u32 v2, v15, 12, v2
	v_and_b32_e32 v3, 1, v14
	v_lshl_or_b32 v2, v3, 6, v2
	v_lshl_add_u32 v142, v16, 1, v2
	v_lshlrev_b32_e32 v2, 15, v11
	v_and_b32_e32 v2, 0xffff0000, v2
	v_lshl_add_u32 v2, v12, 12, v2
	v_and_b32_e32 v3, 1, v11
	v_lshl_or_b32 v2, v3, 6, v2
	s_add_i32 s56, 0, 0x14000
	s_ashr_i32 s54, s36, 31
	v_or_b32_e32 v162, s15, v138
	v_mov_b32_e32 v143, v139
	v_lshl_add_u32 v144, v13, 1, v2
	v_mov_b32_e32 v145, v139
	v_mov_b64_e32 v[146:147], 0x80
	v_mov_b64_e32 v[148:149], 0x7f
	v_add_u32_e32 v163, s55, v159
	v_add_u32_e32 v164, s56, v159
	v_add_u32_e32 v165, 0, v4
	s_movk_i32 s57, 0x1000
	v_mov_b32_e32 v166, 0x358637bd
	v_mov_b32_e32 v167, 0xcf
	s_barrier
	s_branch .LBB0_136

.LBB0_267:
	v_lshrrev_b32_e32 v18, 1, v15
	v_and_b32_e32 v145, 24, v18
	s_lshl_b32 s13, s13, 5
	v_and_b32_e32 v17, 15, v15
	v_lshlrev_b32_e32 v18, 1, v145
	v_lshlrev_b32_e32 v15, 2, v15
	s_and_b32 s35, s13, 0x60
	v_lshl_or_b32 v138, s12, 6, v17
	v_lshl_or_b32 v17, v17, 6, v18
	v_and_b32_e32 v15, 32, v15
	s_lshl_b32 s12, s12, 13
	s_lshl_b32 s13, s35, 7
	v_bitop3_b32 v18, v17, s13, v15 bitop3:0xde
	v_bitop3_b32 v15, v17, s12, v15 bitop3:0xde
	s_mov_b64 s[12:13], 0x80
	s_add_i32 m0, s7, 0x18000
	v_lshl_add_u64 v[8:9], v[8:9], 0, s[12:13]
	s_nop 0
	global_load_lds_dwordx4 v[8:9], off
	v_lshl_add_u64 v[6:7], v[6:7], 0, s[12:13]
	s_add_i32 m0, s7, 0x1a000
	s_add_i32 s39, s7, 0x8000
	s_add_i32 s40, s7, 0xa000
	global_load_lds_dwordx4 v[6:7], off
	v_lshl_add_u64 v[4:5], v[4:5], 0, s[12:13]
	s_mov_b32 m0, s39
	s_add_u32 s22, s8, 0x20080
	global_load_lds_dwordx4 v[4:5], off
	v_lshl_add_u64 v[2:3], v[2:3], 0, s[12:13]
	s_mov_b32 m0, s40
	s_addc_u32 s23, s9, 0
	global_load_lds_dwordx4 v[2:3], off
	s_add_i32 m0, s7, 0x1c000
	v_lshl_add_u64 v[2:3], s[22:23], 0, v[132:133]
	global_load_lds_dwordx4 v[2:3], off
	v_lshl_add_u64 v[2:3], s[22:23], 0, v[136:137]
	s_add_i32 m0, s7, 0x1e000
	s_lshl_b32 s17, s17, 3
	global_load_lds_dwordx4 v[2:3], off
	s_andn2_b32 s17, s17, 31
	s_lshl_b32 s16, s16, 3
	s_or_b32 s16, s17, s16
	s_or_b32 s16, s16, s34
	s_ashr_i32 s17, s16, 31
	s_lshl_b64 s[16:17], s[16:17], 18
	s_add_u32 s16, s4, s16
	s_addc_u32 s17, s5, s17
	v_lshlrev_b32_e32 v2, 13, v13
	s_add_u32 s41, s16, 0x9900100
	v_and_b32_e32 v2, 0xffffc000, v2
	s_addc_u32 s42, s17, 0
	v_lshl_add_u32 v2, v14, 10, v2
	v_and_b32_e32 v3, 1, v13
	v_lshl_or_b32 v2, v3, 6, v2
	s_add_u32 s14, s4, s14
	v_lshl_add_u32 v2, v16, 1, v2
	v_mov_b32_e32 v3, v133
	s_addc_u32 s15, s5, s15
	v_lshl_add_u64 v[2:3], s[14:15], 0, v[2:3]
	s_mov_b64 s[16:17], 0x28320080
	v_lshl_add_u64 v[140:141], v[2:3], 0, s[16:17]
	v_lshlrev_b32_e32 v2, 13, v10
	v_and_b32_e32 v2, 0xffffc000, v2
	v_lshl_add_u32 v2, v11, 10, v2
	v_and_b32_e32 v3, 1, v10
	v_lshl_or_b32 v2, v3, 6, v2
	s_waitcnt vmcnt(8)
	s_barrier
	s_waitcnt vmcnt(6)
	v_lshl_add_u32 v2, v12, 1, v2
	v_mov_b32_e32 v3, v133
	s_add_i32 s25, 0, 0x10000
	s_add_i32 s26, 0, 0x14000
	s_add_i32 s27, 0, 0x18000
	s_add_i32 s30, 0, 0x1c000
	v_lshl_add_u64 v[2:3], s[14:15], 0, v[2:3]
	s_add_i32 s46, s25, s18
	s_add_i32 s48, s26, s18
	s_add_i32 s50, s27, s18
	s_add_i32 s53, s30, s18
	v_lshl_add_u64 v[142:143], v[2:3], 0, s[16:17]
	s_mov_b32 s43, -2
	s_mov_b64 s[16:17], 0
	v_add_u32_e32 v139, s25, v18
	v_add_u32_e32 v146, s26, v18
	v_add_u32_e32 v147, 0, v15
	s_add_i32 s44, s7, 0xc000
	s_add_i32 s45, s7, 0xe000
	s_add_i32 s47, s46, 0x2000
	s_add_i32 s49, s48, 0x2000
	v_add_u32_e32 v148, s27, v18
	v_add_u32_e32 v149, s30, v18
	s_add_i32 s51, s50, 0x2000
	s_add_i32 s54, s53, 0x2000
	v_mov_b32_e32 v2, v133
	v_mov_b32_e32 v3, v133
	v_mov_b32_e32 v4, v133
	v_mov_b32_e32 v5, v133
	v_mov_b32_e32 v6, v133
	v_mov_b32_e32 v7, v133
	v_mov_b32_e32 v8, v133
	v_mov_b32_e32 v9, v133
	v_mov_b32_e32 v10, v133
	v_mov_b32_e32 v11, v133
	v_mov_b32_e32 v12, v133
	v_mov_b32_e32 v13, v133
	v_mov_b32_e32 v18, v133
	v_mov_b32_e32 v19, v133
	v_mov_b32_e32 v20, v133
	v_mov_b32_e32 v21, v133
	v_mov_b32_e32 v26, v133
	v_mov_b32_e32 v27, v133
	v_mov_b32_e32 v28, v133
	v_mov_b32_e32 v29, v133
	v_mov_b32_e32 v34, v133
	v_mov_b32_e32 v35, v133
	v_mov_b32_e32 v36, v133
	v_mov_b32_e32 v37, v133
	v_mov_b32_e32 v42, v133
	v_mov_b32_e32 v43, v133
	v_mov_b32_e32 v44, v133
	v_mov_b32_e32 v45, v133
	v_mov_b32_e32 v50, v133
	v_mov_b32_e32 v51, v133
	v_mov_b32_e32 v52, v133
	v_mov_b32_e32 v53, v133
	v_mov_b32_e32 v14, v133
	v_mov_b32_e32 v15, v133
	v_mov_b32_e32 v16, v133
	v_mov_b32_e32 v17, v133
	v_mov_b32_e32 v22, v133
	v_mov_b32_e32 v23, v133
	v_mov_b32_e32 v24, v133
	v_mov_b32_e32 v25, v133
	v_mov_b32_e32 v30, v133
	v_mov_b32_e32 v31, v133
	v_mov_b32_e32 v32, v133
	v_mov_b32_e32 v33, v133
	v_mov_b32_e32 v38, v133
	v_mov_b32_e32 v39, v133
	v_mov_b32_e32 v40, v133
	v_mov_b32_e32 v41, v133
	v_mov_b32_e32 v46, v133
	v_mov_b32_e32 v47, v133
	v_mov_b32_e32 v48, v133
	v_mov_b32_e32 v49, v133
	v_mov_b32_e32 v54, v133
	v_mov_b32_e32 v55, v133
	v_mov_b32_e32 v56, v133
	v_mov_b32_e32 v57, v133
	v_mov_b32_e32 v58, v133
	v_mov_b32_e32 v59, v133
	v_mov_b32_e32 v60, v133
	v_mov_b32_e32 v61, v133
	v_mov_b32_e32 v62, v133
	v_mov_b32_e32 v63, v133
	v_mov_b32_e32 v64, v133
	v_mov_b32_e32 v65, v133
	v_mov_b32_e32 v66, v133
	v_mov_b32_e32 v67, v133
	v_mov_b32_e32 v68, v133
	v_mov_b32_e32 v69, v133
	v_mov_b32_e32 v70, v133
	v_mov_b32_e32 v71, v133
	v_mov_b32_e32 v72, v133
	v_mov_b32_e32 v73, v133
	v_mov_b32_e32 v74, v133
	v_mov_b32_e32 v75, v133
	v_mov_b32_e32 v76, v133
	v_mov_b32_e32 v77, v133
	v_mov_b32_e32 v82, v133
	v_mov_b32_e32 v83, v133
	v_mov_b32_e32 v84, v133
	v_mov_b32_e32 v85, v133
	v_mov_b32_e32 v90, v133
	v_mov_b32_e32 v91, v133
	v_mov_b32_e32 v92, v133
	v_mov_b32_e32 v93, v133
	v_mov_b32_e32 v98, v133
	v_mov_b32_e32 v99, v133
	v_mov_b32_e32 v100, v133
	v_mov_b32_e32 v101, v133
	v_mov_b32_e32 v106, v133
	v_mov_b32_e32 v107, v133
	v_mov_b32_e32 v108, v133
	v_mov_b32_e32 v109, v133
	v_mov_b32_e32 v114, v133
	v_mov_b32_e32 v115, v133
	v_mov_b32_e32 v116, v133
	v_mov_b32_e32 v117, v133
	v_mov_b32_e32 v78, v133
	v_mov_b32_e32 v79, v133
	v_mov_b32_e32 v80, v133
	v_mov_b32_e32 v81, v133
	v_mov_b32_e32 v86, v133
	v_mov_b32_e32 v87, v133
	v_mov_b32_e32 v88, v133
	v_mov_b32_e32 v89, v133
	v_mov_b32_e32 v94, v133
	v_mov_b32_e32 v95, v133
	v_mov_b32_e32 v96, v133
	v_mov_b32_e32 v97, v133
	v_mov_b32_e32 v102, v133
	v_mov_b32_e32 v103, v133
	v_mov_b32_e32 v104, v133
	v_mov_b32_e32 v105, v133
	v_mov_b32_e32 v110, v133
	v_mov_b32_e32 v111, v133
	v_mov_b32_e32 v112, v133
	v_mov_b32_e32 v113, v133
	v_mov_b32_e32 v118, v133
	v_mov_b32_e32 v119, v133
	v_mov_b32_e32 v120, v133
	v_mov_b32_e32 v121, v133
	v_mov_b32_e32 v122, v133
	v_mov_b32_e32 v123, v133
	v_mov_b32_e32 v124, v133
	v_mov_b32_e32 v125, v133
	v_mov_b32_e32 v126, v133
	v_mov_b32_e32 v127, v133
	v_mov_b32_e32 v128, v133
	v_mov_b32_e32 v129, v133
	s_barrier

.LBB0_273:
	v_lshrrev_b32_e32 v17, 1, v144
	v_and_b32_e32 v143, 24, v17
	v_and_b32_e32 v16, 15, v144
	v_lshlrev_b32_e32 v17, 1, v143
	s_lshl_b32 s13, s13, 5
	v_lshl_or_b32 v142, s12, 6, v16
	v_lshl_or_b32 v16, v16, 6, v17
	v_lshlrev_b32_e32 v17, 2, v144
	s_and_b32 s37, s13, 0x60
	v_and_b32_e32 v17, 32, v17
	s_lshl_b32 s12, s12, 13
	s_lshl_b32 s13, s37, 7
	v_bitop3_b32 v18, v16, s13, v17 bitop3:0xde
	v_bitop3_b32 v16, v16, s12, v17 bitop3:0xde
	s_mov_b64 s[12:13], 0x80
	s_add_i32 m0, s7, 0x18000
	v_lshl_add_u64 v[8:9], v[8:9], 0, s[12:13]
	s_nop 0
	global_load_lds_dwordx4 v[8:9], off
	v_lshl_add_u64 v[6:7], v[6:7], 0, s[12:13]
	s_add_i32 m0, s7, 0x1a000
	s_add_i32 s38, s7, 0x8000
	s_add_i32 s39, s7, 0xa000
	global_load_lds_dwordx4 v[6:7], off
	v_lshl_add_u64 v[4:5], v[4:5], 0, s[12:13]
	s_mov_b32 m0, s38
	s_add_u32 s22, s8, 0x20080
	global_load_lds_dwordx4 v[4:5], off
	v_lshl_add_u64 v[2:3], v[2:3], 0, s[12:13]
	s_mov_b32 m0, s39
	s_addc_u32 s23, s9, 0
	global_load_lds_dwordx4 v[2:3], off
	s_add_i32 m0, s7, 0x1c000
	v_lshl_add_u64 v[2:3], s[22:23], 0, v[130:131]
	global_load_lds_dwordx4 v[2:3], off
	v_lshl_add_u64 v[2:3], s[22:23], 0, v[136:137]
	s_add_i32 m0, s7, 0x1e000
	s_add_u32 s14, s4, s14
	global_load_lds_dwordx4 v[2:3], off
	s_addc_u32 s15, s5, s15
	s_add_u32 s40, s14, 0x28b00100
	s_addc_u32 s41, s15, 0
	s_lshl_b32 s14, s17, 3
	s_andn2_b32 s14, s14, 31
	s_lshl_b32 s15, s16, 3
	s_or_b32 s14, s14, s15
	s_or_b32 s14, s14, s33
	v_lshlrev_b32_e32 v2, 13, v13
	s_ashr_i32 s15, s14, 31
	v_and_b32_e32 v2, 0xffffc000, v2
	s_lshl_b64 s[14:15], s[14:15], 18
	v_lshl_add_u32 v2, v14, 10, v2
	v_and_b32_e32 v3, 1, v13
	v_lshl_or_b32 v2, v3, 6, v2
	s_add_u32 s14, s4, s14
	v_lshl_add_u32 v2, v15, 1, v2
	v_mov_b32_e32 v3, v131
	s_addc_u32 s15, s5, s15
	v_lshl_add_u64 v[2:3], s[14:15], 0, v[2:3]
	s_mov_b64 s[16:17], 0xf920080
	v_lshl_add_u64 v[138:139], v[2:3], 0, s[16:17]
	v_lshlrev_b32_e32 v2, 13, v10
	v_and_b32_e32 v2, 0xffffc000, v2
	v_lshl_add_u32 v2, v11, 10, v2
	v_and_b32_e32 v3, 1, v10
	v_lshl_or_b32 v2, v3, 6, v2
	s_waitcnt vmcnt(8)
	s_barrier
	s_waitcnt vmcnt(6)
	v_lshl_add_u32 v2, v12, 1, v2
	v_mov_b32_e32 v3, v131
	v_lshl_add_u64 v[2:3], s[14:15], 0, v[2:3]
	v_add_u32_e32 v144, s25, v18
	v_add_u32_e32 v145, s26, v18
	s_add_i32 s25, s25, s18
	s_add_i32 s26, s26, s18
	v_add_u32_e32 v147, s27, v18
	v_add_u32_e32 v148, s30, v18
	s_add_i32 s27, s27, s18
	s_add_i32 s30, s30, s18
	v_lshl_add_u64 v[140:141], v[2:3], 0, s[16:17]
	s_mov_b32 s42, -2
	s_mov_b64 s[16:17], 0
	v_add_u32_e32 v146, 0, v16
	s_add_i32 s43, s7, 0xc000
	s_add_i32 s44, s7, 0xe000
	s_add_i32 s45, s25, 0x2000
	s_add_i32 s46, s26, 0x2000
	s_add_i32 s47, s27, 0x2000
	s_add_i32 s48, s30, 0x2000
	v_mov_b32_e32 v2, v131
	v_mov_b32_e32 v3, v131
	v_mov_b32_e32 v4, v131
	v_mov_b32_e32 v5, v131
	v_mov_b32_e32 v6, v131
	v_mov_b32_e32 v7, v131
	v_mov_b32_e32 v8, v131
	v_mov_b32_e32 v9, v131
	v_mov_b32_e32 v10, v131
	v_mov_b32_e32 v11, v131
	v_mov_b32_e32 v12, v131
	v_mov_b32_e32 v13, v131
	v_mov_b32_e32 v18, v131
	v_mov_b32_e32 v19, v131
	v_mov_b32_e32 v20, v131
	v_mov_b32_e32 v21, v131
	v_mov_b32_e32 v26, v131
	v_mov_b32_e32 v27, v131
	v_mov_b32_e32 v28, v131
	v_mov_b32_e32 v29, v131
	v_mov_b32_e32 v34, v131
	v_mov_b32_e32 v35, v131
	v_mov_b32_e32 v36, v131
	v_mov_b32_e32 v37, v131
	v_mov_b32_e32 v42, v131
	v_mov_b32_e32 v43, v131
	v_mov_b32_e32 v44, v131
	v_mov_b32_e32 v45, v131
	v_mov_b32_e32 v50, v131
	v_mov_b32_e32 v51, v131
	v_mov_b32_e32 v52, v131
	v_mov_b32_e32 v53, v131
	v_mov_b32_e32 v14, v131
	v_mov_b32_e32 v15, v131
	v_mov_b32_e32 v16, v131
	v_mov_b32_e32 v17, v131
	v_mov_b32_e32 v22, v131
	v_mov_b32_e32 v23, v131
	v_mov_b32_e32 v24, v131
	v_mov_b32_e32 v25, v131
	v_mov_b32_e32 v30, v131
	v_mov_b32_e32 v31, v131
	v_mov_b32_e32 v32, v131
	v_mov_b32_e32 v33, v131
	v_mov_b32_e32 v38, v131
	v_mov_b32_e32 v39, v131
	v_mov_b32_e32 v40, v131
	v_mov_b32_e32 v41, v131
	v_mov_b32_e32 v46, v131
	v_mov_b32_e32 v47, v131
	v_mov_b32_e32 v48, v131
	v_mov_b32_e32 v49, v131
	v_mov_b32_e32 v54, v131
	v_mov_b32_e32 v55, v131
	v_mov_b32_e32 v56, v131
	v_mov_b32_e32 v57, v131
	v_mov_b32_e32 v58, v131
	v_mov_b32_e32 v59, v131
	v_mov_b32_e32 v60, v131
	v_mov_b32_e32 v61, v131
	v_mov_b32_e32 v62, v131
	v_mov_b32_e32 v63, v131
	v_mov_b32_e32 v64, v131
	v_mov_b32_e32 v65, v131
	v_mov_b32_e32 v66, v131
	v_mov_b32_e32 v67, v131
	v_mov_b32_e32 v68, v131
	v_mov_b32_e32 v69, v131
	v_mov_b32_e32 v70, v131
	v_mov_b32_e32 v71, v131
	v_mov_b32_e32 v72, v131
	v_mov_b32_e32 v73, v131
	v_mov_b32_e32 v74, v131
	v_mov_b32_e32 v75, v131
	v_mov_b32_e32 v76, v131
	v_mov_b32_e32 v77, v131
	v_mov_b32_e32 v82, v131
	v_mov_b32_e32 v83, v131
	v_mov_b32_e32 v84, v131
	v_mov_b32_e32 v85, v131
	v_mov_b32_e32 v90, v131
	v_mov_b32_e32 v91, v131
	v_mov_b32_e32 v92, v131
	v_mov_b32_e32 v93, v131
	v_mov_b32_e32 v98, v131
	v_mov_b32_e32 v99, v131
	v_mov_b32_e32 v100, v131
	v_mov_b32_e32 v101, v131
	v_mov_b32_e32 v106, v131
	v_mov_b32_e32 v107, v131
	v_mov_b32_e32 v108, v131
	v_mov_b32_e32 v109, v131
	v_mov_b32_e32 v114, v131
	v_mov_b32_e32 v115, v131
	v_mov_b32_e32 v116, v131
	v_mov_b32_e32 v117, v131
	v_mov_b32_e32 v78, v131
	v_mov_b32_e32 v79, v131
	v_mov_b32_e32 v80, v131
	v_mov_b32_e32 v81, v131
	v_mov_b32_e32 v86, v131
	v_mov_b32_e32 v87, v131
	v_mov_b32_e32 v88, v131
	v_mov_b32_e32 v89, v131
	v_mov_b32_e32 v94, v131
	v_mov_b32_e32 v95, v131
	v_mov_b32_e32 v96, v131
	v_mov_b32_e32 v97, v131
	v_mov_b32_e32 v102, v131
	v_mov_b32_e32 v103, v131
	v_mov_b32_e32 v104, v131
	v_mov_b32_e32 v105, v131
	v_mov_b32_e32 v110, v131
	v_mov_b32_e32 v111, v131
	v_mov_b32_e32 v112, v131
	v_mov_b32_e32 v113, v131
	v_mov_b32_e32 v118, v131
	v_mov_b32_e32 v119, v131
	v_mov_b32_e32 v120, v131
	v_mov_b32_e32 v121, v131
	v_mov_b32_e32 v122, v131
	v_mov_b32_e32 v123, v131
	v_mov_b32_e32 v124, v131
	v_mov_b32_e32 v125, v131
	v_mov_b32_e32 v126, v131
	v_mov_b32_e32 v127, v131
	v_mov_b32_e32 v128, v131
	v_mov_b32_e32 v129, v131
	s_barrier

.LBB0_336:
	s_sext_i32_i16 s30, s20
	s_add_u32 s20, s24, 0x2d300000
	s_addc_u32 s21, s25, 0
	v_bfe_u32 v21, v18, 4, 2
	s_lshl_b32 s16, s16, 5
	v_and_b32_e32 v19, 15, v18
	v_lshlrev_b32_e32 v20, 3, v21
	v_lshlrev_b32_e32 v21, 4, v21
	v_lshlrev_b32_e32 v18, 2, v18
	s_and_b32 s19, s16, 0x60
	v_lshl_or_b32 v145, s17, 6, v19
	v_lshl_or_b32 v19, v19, 6, v21
	s_lshl_b32 s17, s17, 13
	v_and_b32_e32 v18, 32, v18
	s_lshl_b32 s16, s19, 7
	s_add_i32 m0, s12, 0x18000
	v_lshl_add_u64 v[10:11], v[10:11], 0, s[68:69]
	v_bitop3_b32 v22, v19, s17, v18 bitop3:0xde
	v_bitop3_b32 v149, v19, s16, v18 bitop3:0xde
	s_nop 0
	global_load_lds_dwordx4 v[10:11], off
	v_lshl_add_u64 v[8:9], v[8:9], 0, s[68:69]
	s_add_i32 m0, s12, 0x1a000
	s_add_i32 s16, s12, 0x8000
	s_add_i32 s17, s12, 0xa000
	global_load_lds_dwordx4 v[8:9], off
	v_lshl_add_u64 v[4:5], v[4:5], 0, s[68:69]
	s_mov_b32 m0, s16
	s_add_u32 s22, s44, 0x80080
	global_load_lds_dwordx4 v[4:5], off
	v_lshl_add_u64 v[4:5], v[6:7], 0, s[68:69]
	s_mov_b32 m0, s17
	s_addc_u32 s23, s45, 0
	global_load_lds_dwordx4 v[4:5], off
	s_add_i32 m0, s12, 0x1c000
	v_lshl_add_u64 v[4:5], s[22:23], 0, v[2:3]
	global_load_lds_dwordx4 v[4:5], off
	v_lshl_add_u64 v[4:5], s[22:23], 0, v[0:1]
	s_add_i32 m0, s12, 0x1e000
	v_cmp_lt_i32_e32 vcc, v236, v237
	global_load_lds_dwordx4 v[4:5], off
	s_nop 0
	v_cndmask_b32_e32 v4, v234, v236, vcc
	v_cmp_lt_i32_e32 vcc, v252, v237
	v_lshlrev_b32_e32 v153, 2, v4
	v_mov_b32_e32 v21, v3
	v_cndmask_b32_e32 v4, v234, v252, vcc
	v_lshlrev_b32_e32 v159, 2, v4
	v_lshl_add_u64 v[4:5], s[24:25], 0, v[20:21]
	s_mov_b64 s[24:25], 0x800000
	v_lshl_add_u64 v[136:137], v[4:5], 0, s[24:25]
	v_lshlrev_b32_e32 v4, 15, v12
	v_and_b32_e32 v4, 0xffff0000, v4
	v_lshl_add_u32 v4, v13, 12, v4
	v_and_b32_e32 v5, 1, v12
	v_lshl_or_b32 v4, v5, 6, v4
	v_lshl_add_u32 v138, v14, 1, v4
	v_lshlrev_b32_e32 v4, 15, v16
	v_and_b32_e32 v4, 0xffff0000, v4
	s_waitcnt vmcnt(8)
	s_barrier
	s_waitcnt vmcnt(6)
	v_lshl_add_u32 v4, v15, 12, v4
	v_and_b32_e32 v5, 1, v16
	s_cmpk_lt_u32 s18, 0x100
	v_lshl_or_b32 v4, v5, 6, v4
	s_cselect_b64 s[22:23], -1, 0
	s_ashr_i32 s18, s4, 31
	v_or_b32_e32 v163, s19, v20
	v_mov_b32_e32 v139, v3
	v_lshl_add_u32 v140, v17, 1, v4
	v_mov_b32_e32 v141, v3
	s_mov_b32 s19, 0
	v_add_u32_e32 v167, 0, v22
	s_barrier
	s_branch .LBB0_339

.LBB0_735:
	s_add_u32 s26, s2, 0x22100000
	s_addc_u32 s27, s3, 0
	s_add_u32 s40, s34, 0x2000
	s_addc_u32 s41, s35, 0
	s_lshl_b64 s[8:9], s[72:73], 2
	s_add_u32 s8, s2, s8
	s_addc_u32 s9, s3, s9
	s_add_u32 s42, s8, 0x100000
	s_addc_u32 s43, s9, 0
	s_add_u32 s44, s2, 0x800000
	v_and_b32_e32 v19, 48, v18
	v_lshlrev_b32_e32 v20, 6, v18
	s_movk_i32 s9, 0x3c0
	v_lshlrev_b32_e32 v18, 2, v18
	s_addc_u32 s45, s3, 0
	s_and_b32 s10, s7, 3
	s_lshl_b32 s8, s5, 13
	v_and_or_b32 v19, v20, s9, v19
	v_and_b32_e32 v18, 32, v18
	s_add_i32 m0, s21, 0x18000
	v_lshl_add_u64 v[10:11], v[10:11], 0, s[68:69]
	s_lshl_b32 s87, s5, 6
	v_bitop3_b32 v20, v19, s8, v18 bitop3:0xde
	s_lshl_b32 s8, s10, 12
	s_lshl_b32 s88, s10, 5
	s_nop 0
	global_load_lds_dwordx4 v[10:11], off
	v_lshl_add_u64 v[8:9], v[8:9], 0, s[68:69]
	s_add_i32 m0, s21, 0x1a000
	s_add_i32 s89, s21, 0x8000
	s_add_i32 s90, s21, 0xa000
	v_bitop3_b32 v230, v19, s8, v18 bitop3:0xde
	global_load_lds_dwordx4 v[8:9], off
	v_lshl_add_u64 v[4:5], v[4:5], 0, s[68:69]
	s_mov_b32 m0, s89
	s_add_u32 s8, s36, 0x80080
	global_load_lds_dwordx4 v[4:5], off
	v_lshl_add_u64 v[4:5], v[6:7], 0, s[68:69]
	s_mov_b32 m0, s90
	s_addc_u32 s9, s37, 0
	global_load_lds_dwordx4 v[4:5], off
	s_add_i32 m0, s21, 0x1c000
	v_lshl_add_u64 v[4:5], s[8:9], 0, v[2:3]
	global_load_lds_dwordx4 v[4:5], off
	v_lshl_add_u64 v[4:5], s[8:9], 0, v[218:219]
	s_add_i32 m0, s21, 0x1e000
	v_cmp_lt_i32_e32 vcc, v236, v237
	global_load_lds_dwordx4 v[4:5], off
	s_nop 0
	v_cndmask_b32_e32 v4, v234, v236, vcc
	v_cmp_lt_i32_e32 vcc, v252, v237
	v_lshlrev_b32_e32 v231, 2, v4
	v_and_b32_e32 v5, 1, v15
	v_cndmask_b32_e32 v4, v234, v252, vcc
	v_lshlrev_b32_e32 v242, 2, v4
	v_lshlrev_b32_e32 v4, 15, v15
	v_and_b32_e32 v4, 0xffff0000, v4
	v_lshl_add_u32 v4, v16, 12, v4
	v_lshl_or_b32 v4, v5, 6, v4
	s_cmpk_lt_u32 s6, 0x100
	v_lshl_add_u32 v220, v17, 1, v4
	v_lshlrev_b32_e32 v4, 15, v12
	s_cselect_b64 s[46:47], -1, 0
	s_lshl_b32 s6, s10, 2
	v_and_b32_e32 v4, 0xffff0000, v4
	s_waitcnt vmcnt(8)
	s_barrier
	s_waitcnt vmcnt(6)
	s_add_i32 s91, s6, 0
	v_lshl_add_u32 v4, v13, 12, v4
	v_and_b32_e32 v5, 1, v12
	s_add_i32 s91, s91, 0x20400
	s_lshl_b32 s5, s5, 10
	v_lshl_or_b32 v4, v5, 6, v4
	s_add_i32 s92, s91, s5
	s_lshl_b32 s93, s7, 5
	s_or_b32 s66, s4, 32
	v_mov_b32_e32 v221, v3
	v_lshl_add_u32 v222, v14, 1, v4
	v_mov_b32_e32 v223, v3
	s_mov_b64 s[52:53], -1
	v_add_u32_e32 v243, 0, v20
	s_mov_b32 s54, s20
	s_barrier
	s_branch .LBB0_738

.LBB0_853:
	v_and_b32_e32 v203, 15, v16
	v_bfe_u32 v201, v16, 4, 2
	s_and_b32 s5, s5, 3
	v_lshlrev_b32_e32 v16, 4, v201
	v_lshlrev_b32_e32 v202, 2, v203
	v_lshl_or_b32 v16, v203, 6, v16
	v_and_b32_e32 v19, 32, v202
	s_lshl_b32 s14, s8, 13
	s_lshl_b32 s15, s5, 12
	s_add_i32 m0, s10, 0x18000
	v_lshl_add_u64 v[10:11], v[10:11], 0, s[68:69]
	v_bitop3_b32 v140, v16, s15, v19 bitop3:0xde
	v_bitop3_b32 v16, v16, s14, v19 bitop3:0xde
	s_nop 0
	global_load_lds_dwordx4 v[10:11], off
	v_lshl_add_u64 v[8:9], v[8:9], 0, s[68:69]
	s_add_i32 m0, s10, 0x1a000
	s_add_i32 s14, s10, 0x8000
	s_add_i32 s15, s10, 0xa000
	global_load_lds_dwordx4 v[8:9], off
	v_lshl_add_u64 v[6:7], v[6:7], 0, s[68:69]
	s_mov_b32 m0, s14
	s_add_u32 s16, s20, 0x80080
	global_load_lds_dwordx4 v[6:7], off
	v_lshl_add_u64 v[4:5], v[4:5], 0, s[68:69]
	s_mov_b32 m0, s15
	s_addc_u32 s17, s21, 0
	global_load_lds_dwordx4 v[4:5], off
	s_add_i32 m0, s10, 0x1c000
	v_lshl_add_u64 v[4:5], s[16:17], 0, v[2:3]
	global_load_lds_dwordx4 v[4:5], off
	v_lshl_add_u64 v[4:5], s[16:17], 0, v[134:135]
	s_add_i32 m0, s10, 0x1e000
	v_readlane_b32 s16, v254, 25
	global_load_lds_dwordx4 v[4:5], off
	v_readlane_b32 s17, v254, 26
	s_add_u32 s16, s16, s24
	s_addc_u32 s17, s17, s25
	s_add_u32 s16, s2, s16
	s_addc_u32 s17, s3, s17
	s_and_b32 s18, s18, 7
	s_lshl_b32 s18, s18, 23
	s_lshl_b32 s19, s19, 20
	v_lshlrev_b32_e32 v4, 15, v15
	s_or_b32 s18, s18, s19
	v_and_b32_e32 v4, 0xffff0000, v4
	s_add_u32 s18, s2, s18
	v_lshl_add_u32 v4, v17, 12, v4
	v_and_b32_e32 v5, 1, v15
	s_addc_u32 s19, s3, 0
	v_lshl_or_b32 v4, v5, 6, v4
	s_add_u32 s24, s18, 0x22180080
	v_lshl_add_u32 v4, v18, 1, v4
	v_mov_b32_e32 v5, v3
	s_addc_u32 s25, s19, 0
	v_lshl_add_u64 v[136:137], s[24:25], 0, v[4:5]
	v_lshlrev_b32_e32 v4, 15, v12
	v_and_b32_e32 v4, 0xffff0000, v4
	v_lshl_add_u32 v4, v13, 12, v4
	v_and_b32_e32 v5, 1, v12
	v_lshl_or_b32 v4, v5, 6, v4
	s_waitcnt vmcnt(8)
	s_barrier
	s_waitcnt vmcnt(6)
	v_lshl_add_u32 v4, v14, 1, v4
	v_mov_b32_e32 v5, v3
	v_lshl_add_u64 v[138:139], s[24:25], 0, v[4:5]
	v_mov_b32_e32 v4, 0
	v_lshl_or_b32 v200, s8, 6, v203
	s_mov_b32 s28, -2
	s_mov_b64 s[24:25], 0
	v_add_u32_e32 v141, 0, v16
	v_mov_b32_e32 v5, v4
	v_mov_b32_e32 v6, v4
	v_mov_b32_e32 v7, v4
	v_mov_b32_e32 v8, v4
	v_mov_b32_e32 v9, v4
	v_mov_b32_e32 v10, v4
	v_mov_b32_e32 v11, v4
	v_mov_b32_e32 v20, v4
	v_mov_b32_e32 v21, v4
	v_mov_b32_e32 v22, v4
	v_mov_b32_e32 v23, v4
	v_mov_b32_e32 v24, v4
	v_mov_b32_e32 v25, v4
	v_mov_b32_e32 v26, v4
	v_mov_b32_e32 v27, v4
	v_mov_b32_e32 v36, v4
	v_mov_b32_e32 v37, v4
	v_mov_b32_e32 v38, v4
	v_mov_b32_e32 v39, v4
	v_mov_b32_e32 v40, v4
	v_mov_b32_e32 v41, v4
	v_mov_b32_e32 v42, v4
	v_mov_b32_e32 v43, v4
	v_mov_b32_e32 v52, v4
	v_mov_b32_e32 v53, v4
	v_mov_b32_e32 v54, v4
	v_mov_b32_e32 v55, v4
	v_mov_b32_e32 v56, v4
	v_mov_b32_e32 v57, v4
	v_mov_b32_e32 v58, v4
	v_mov_b32_e32 v59, v4
	v_mov_b32_e32 v12, v4
	v_mov_b32_e32 v13, v4
	v_mov_b32_e32 v14, v4
	v_mov_b32_e32 v15, v4
	v_mov_b32_e32 v16, v4
	v_mov_b32_e32 v17, v4
	v_mov_b32_e32 v18, v4
	v_mov_b32_e32 v19, v4
	v_mov_b32_e32 v28, v4
	v_mov_b32_e32 v29, v4
	v_mov_b32_e32 v30, v4
	v_mov_b32_e32 v31, v4
	v_mov_b32_e32 v32, v4
	v_mov_b32_e32 v33, v4
	v_mov_b32_e32 v34, v4
	v_mov_b32_e32 v35, v4
	v_mov_b32_e32 v44, v4
	v_mov_b32_e32 v45, v4
	v_mov_b32_e32 v46, v4
	v_mov_b32_e32 v47, v4
	v_mov_b32_e32 v48, v4
	v_mov_b32_e32 v49, v4
	v_mov_b32_e32 v50, v4
	v_mov_b32_e32 v51, v4
	v_mov_b32_e32 v60, v4
	v_mov_b32_e32 v61, v4
	v_mov_b32_e32 v62, v4
	v_mov_b32_e32 v63, v4
	v_mov_b32_e32 v64, v4
	v_mov_b32_e32 v65, v4
	v_mov_b32_e32 v66, v4
	v_mov_b32_e32 v67, v4
	v_mov_b32_e32 v68, v4
	v_mov_b32_e32 v69, v4
	v_mov_b32_e32 v70, v4
	v_mov_b32_e32 v71, v4
	v_mov_b32_e32 v72, v4
	v_mov_b32_e32 v73, v4
	v_mov_b32_e32 v74, v4
	v_mov_b32_e32 v75, v4
	v_mov_b32_e32 v84, v4
	v_mov_b32_e32 v85, v4
	v_mov_b32_e32 v86, v4
	v_mov_b32_e32 v87, v4
	v_mov_b32_e32 v88, v4
	v_mov_b32_e32 v89, v4
	v_mov_b32_e32 v90, v4
	v_mov_b32_e32 v91, v4
	v_mov_b32_e32 v100, v4
	v_mov_b32_e32 v101, v4
	v_mov_b32_e32 v102, v4
	v_mov_b32_e32 v103, v4
	v_mov_b32_e32 v104, v4
	v_mov_b32_e32 v105, v4
	v_mov_b32_e32 v106, v4
	v_mov_b32_e32 v107, v4
	v_mov_b32_e32 v116, v4
	v_mov_b32_e32 v117, v4
	v_mov_b32_e32 v118, v4
	v_mov_b32_e32 v119, v4
	v_mov_b32_e32 v120, v4
	v_mov_b32_e32 v121, v4
	v_mov_b32_e32 v122, v4
	v_mov_b32_e32 v123, v4
	v_mov_b32_e32 v76, v4
	v_mov_b32_e32 v77, v4
	v_mov_b32_e32 v78, v4
	v_mov_b32_e32 v79, v4
	v_mov_b32_e32 v80, v4
	v_mov_b32_e32 v81, v4
	v_mov_b32_e32 v82, v4
	v_mov_b32_e32 v83, v4
	v_mov_b32_e32 v92, v4
	v_mov_b32_e32 v93, v4
	v_mov_b32_e32 v94, v4
	v_mov_b32_e32 v95, v4
	v_mov_b32_e32 v96, v4
	v_mov_b32_e32 v97, v4
	v_mov_b32_e32 v98, v4
	v_mov_b32_e32 v99, v4
	v_mov_b32_e32 v108, v4
	v_mov_b32_e32 v109, v4
	v_mov_b32_e32 v110, v4
	v_mov_b32_e32 v111, v4
	v_mov_b32_e32 v112, v4
	v_mov_b32_e32 v113, v4
	v_mov_b32_e32 v114, v4
	v_mov_b32_e32 v115, v4
	v_mov_b32_e32 v124, v4
	v_mov_b32_e32 v125, v4
	v_mov_b32_e32 v126, v4
	v_mov_b32_e32 v127, v4
	v_mov_b32_e32 v128, v4
	v_mov_b32_e32 v129, v4
	v_mov_b32_e32 v130, v4
	v_mov_b32_e32 v131, v4
	s_barrier

.LBB0_943:
	s_add_u32 s24, s2, 0x22100000
	s_addc_u32 s25, s3, 0
	s_add_u32 s26, s34, 0x8000
	s_addc_u32 s27, s35, 0
	s_lshl_b64 s[8:9], s[72:73], 2
	s_add_u32 s8, s2, s8
	s_addc_u32 s9, s3, s9
	s_add_u32 s42, s8, 0x180000
	s_addc_u32 s43, s9, 0
	s_add_u32 s44, s2, 0x800000
	v_and_b32_e32 v19, 48, v18
	v_lshlrev_b32_e32 v20, 6, v18
	s_movk_i32 s9, 0x3c0
	v_lshlrev_b32_e32 v18, 2, v18
	s_addc_u32 s45, s3, 0
	s_and_b32 s10, s7, 3
	s_lshl_b32 s8, s5, 13
	v_and_or_b32 v19, v20, s9, v19
	v_and_b32_e32 v18, 32, v18
	s_add_i32 m0, s71, 0x18000
	v_lshl_add_u64 v[10:11], v[10:11], 0, s[68:69]
	s_lshl_b32 s83, s5, 6
	v_bitop3_b32 v20, v19, s8, v18 bitop3:0xde
	s_lshl_b32 s8, s10, 12
	s_lshl_b32 s84, s10, 5
	s_nop 0
	global_load_lds_dwordx4 v[10:11], off
	v_lshl_add_u64 v[8:9], v[8:9], 0, s[68:69]
	s_add_i32 m0, s71, 0x1a000
	s_add_i32 s85, s71, 0x8000
	s_add_i32 s87, s71, 0xa000
	v_bitop3_b32 v230, v19, s8, v18 bitop3:0xde
	global_load_lds_dwordx4 v[8:9], off
	v_lshl_add_u64 v[4:5], v[4:5], 0, s[68:69]
	s_mov_b32 m0, s85
	s_add_u32 s8, s38, 0x40080
	global_load_lds_dwordx4 v[4:5], off
	v_lshl_add_u64 v[4:5], v[6:7], 0, s[68:69]
	s_mov_b32 m0, s87
	s_addc_u32 s9, s39, 0
	global_load_lds_dwordx4 v[4:5], off
	s_add_i32 m0, s71, 0x1c000
	v_lshl_add_u64 v[4:5], s[8:9], 0, v[2:3]
	global_load_lds_dwordx4 v[4:5], off
	v_lshl_add_u64 v[4:5], s[8:9], 0, v[218:219]
	s_add_i32 m0, s71, 0x1e000
	v_cmp_lt_i32_e32 vcc, v236, v237
	global_load_lds_dwordx4 v[4:5], off
	s_nop 0
	v_cndmask_b32_e32 v4, v234, v236, vcc
	v_cmp_lt_i32_e32 vcc, v252, v237
	v_lshlrev_b32_e32 v231, 2, v4
	v_and_b32_e32 v5, 1, v15
	v_cndmask_b32_e32 v4, v234, v252, vcc
	v_lshlrev_b32_e32 v242, 2, v4
	v_lshlrev_b32_e32 v4, 14, v15
	v_and_b32_e32 v4, 0xffff8000, v4
	v_lshl_add_u32 v4, v16, 11, v4
	v_lshl_or_b32 v4, v5, 6, v4
	s_cmpk_lt_u32 s6, 0x100
	v_lshl_add_u32 v220, v17, 1, v4
	v_lshlrev_b32_e32 v4, 14, v12
	s_cselect_b64 s[46:47], -1, 0
	s_lshl_b32 s6, s10, 2
	v_and_b32_e32 v4, 0xffff8000, v4
	s_waitcnt vmcnt(8)
	s_barrier
	s_waitcnt vmcnt(6)
	s_add_i32 s66, s6, 0
	v_lshl_add_u32 v4, v13, 11, v4
	v_and_b32_e32 v5, 1, v12
	s_add_i32 s66, s66, 0x20400
	s_lshl_b32 s5, s5, 10
	v_lshl_or_b32 v4, v5, 6, v4
	s_add_i32 s88, s66, s5
	s_lshl_b32 s89, s7, 5
	s_or_b32 s48, s4, 32
	s_add_i32 s50, s20, 8
	v_mov_b32_e32 v221, v3
	v_lshl_add_u32 v222, v14, 1, v4
	v_mov_b32_e32 v223, v3
	s_mov_b64 s[56:57], -1
	v_add_u32_e32 v243, 0, v20
	s_barrier
	s_branch .LBB0_946

.LBB0_1060:
	s_sext_i32_i16 s4, s20
	s_add_u32 s20, s24, 0x2d300000
	s_addc_u32 s21, s25, 0
	v_bfe_u32 v21, v18, 4, 2
	s_lshl_b32 s6, s6, 5
	v_and_b32_e32 v19, 15, v18
	v_lshlrev_b32_e32 v20, 3, v21
	v_lshlrev_b32_e32 v21, 4, v21
	v_lshlrev_b32_e32 v18, 2, v18
	s_and_b32 s8, s6, 0x60
	s_add_i32 m0, s60, 0x18000
	v_lshl_add_u64 v[10:11], v[10:11], 0, s[68:69]
	v_lshl_or_b32 v161, s7, 6, v19
	v_lshl_or_b32 v19, v19, 6, v21
	s_lshl_b32 s7, s7, 13
	v_and_b32_e32 v18, 32, v18
	s_lshl_b32 s6, s8, 7
	s_nop 0
	global_load_lds_dwordx4 v[10:11], off
	v_lshl_add_u64 v[8:9], v[8:9], 0, s[68:69]
	s_add_i32 m0, s60, 0x1a000
	s_add_i32 s64, s60, 0x8000
	s_add_i32 s65, s60, 0xa000
	v_bitop3_b32 v163, v19, s6, v18 bitop3:0xde
	global_load_lds_dwordx4 v[8:9], off
	v_lshl_add_u64 v[4:5], v[4:5], 0, s[68:69]
	s_mov_b32 m0, s64
	s_add_u32 s6, s44, 0x80080
	v_bitop3_b32 v22, v19, s7, v18 bitop3:0xde
	global_load_lds_dwordx4 v[4:5], off
	v_lshl_add_u64 v[4:5], v[6:7], 0, s[68:69]
	s_mov_b32 m0, s65
	s_addc_u32 s7, s45, 0
	global_load_lds_dwordx4 v[4:5], off
	s_add_i32 m0, s60, 0x1c000
	v_lshl_add_u64 v[4:5], s[6:7], 0, v[2:3]
	global_load_lds_dwordx4 v[4:5], off
	v_lshl_add_u64 v[4:5], s[6:7], 0, v[0:1]
	s_add_i32 m0, s60, 0x1e000
	v_cmp_lt_i32_e32 vcc, v236, v237
	global_load_lds_dwordx4 v[4:5], off
	s_nop 0
	v_cndmask_b32_e32 v4, v234, v236, vcc
	v_cmp_lt_i32_e32 vcc, v252, v237
	v_lshlrev_b32_e32 v164, 2, v4
	v_mov_b32_e32 v21, v3
	v_cndmask_b32_e32 v4, v234, v252, vcc
	v_lshlrev_b32_e32 v165, 2, v4
	v_lshl_add_u64 v[4:5], s[24:25], 0, v[20:21]
	s_mov_b64 s[6:7], 0x800000
	v_lshl_add_u64 v[136:137], v[4:5], 0, s[6:7]
	v_lshlrev_b32_e32 v4, 15, v12
	v_and_b32_e32 v4, 0xffff0000, v4
	v_lshl_add_u32 v4, v13, 12, v4
	v_and_b32_e32 v5, 1, v12
	v_lshl_or_b32 v4, v5, 6, v4
	v_lshl_add_u32 v138, v14, 1, v4
	v_lshlrev_b32_e32 v4, 15, v16
	v_and_b32_e32 v4, 0xffff0000, v4
	s_waitcnt vmcnt(8)
	s_barrier
	s_waitcnt vmcnt(6)
	v_lshl_add_u32 v4, v15, 12, v4
	v_and_b32_e32 v5, 1, v16
	s_cmpk_lt_u32 s5, 0x100
	v_lshl_or_b32 v4, v5, 6, v4
	s_cselect_b64 s[22:23], -1, 0
	s_ashr_i32 s70, s50, 31
	v_or_b32_e32 v166, s8, v20
	v_mov_b32_e32 v139, v3
	v_lshl_add_u32 v140, v17, 1, v4
	v_mov_b32_e32 v141, v3
	s_mov_b32 s71, 0
	v_add_u32_e32 v167, 0, v22
	s_barrier
	s_branch .LBB0_1063

.LBB0_1126:
	s_add_u32 s24, s2, 0x22100000
	s_addc_u32 s25, s3, 0
	v_readlane_b32 s8, v253, 0
	s_cmp_eq_u32 s12, 3
	v_readlane_b32 s10, v253, 2
	v_readlane_b32 s11, v253, 3
	v_readlane_b32 s9, v253, 1
	s_cselect_b32 s27, s11, 0
	s_cselect_b32 s26, s10, 0
	s_add_u32 s46, s34, 0xc000
	s_addc_u32 s47, s35, 0
	s_lshl_b64 s[8:9], s[72:73], 2
	s_add_u32 s8, s2, s8
	s_addc_u32 s9, s3, s9
	s_add_u32 s48, s8, 0x200000
	s_addc_u32 s49, s9, 0
	s_add_u32 s50, s2, 0x800000
	v_and_b32_e32 v21, 48, v20
	v_lshlrev_b32_e32 v22, 6, v20
	s_movk_i32 s9, 0x3c0
	v_lshlrev_b32_e32 v20, 2, v20
	s_addc_u32 s51, s3, 0
	s_and_b32 s10, s7, 3
	s_lshl_b32 s8, s5, 13
	v_and_or_b32 v21, v22, s9, v21
	v_and_b32_e32 v20, 32, v20
	s_add_i32 m0, s83, 0x18000
	v_lshl_add_u64 v[10:11], v[10:11], 0, s[68:69]
	s_lshl_b32 s66, s5, 6
	v_bitop3_b32 v22, v21, s8, v20 bitop3:0xde
	s_lshl_b32 s8, s10, 12
	s_lshl_b32 s67, s10, 5
	s_nop 0
	global_load_lds_dwordx4 v[10:11], off
	v_lshl_add_u64 v[8:9], v[8:9], 0, s[68:69]
	s_add_i32 m0, s83, 0x1a000
	s_add_i32 s72, s83, 0x8000
	s_add_i32 s88, s83, 0xa000
	v_bitop3_b32 v242, v21, s8, v20 bitop3:0xde
	global_load_lds_dwordx4 v[8:9], off
	v_lshl_add_u64 v[4:5], v[4:5], 0, s[68:69]
	s_mov_b32 m0, s72
	s_add_u32 s8, s40, 0x160080
	global_load_lds_dwordx4 v[4:5], off
	v_lshl_add_u64 v[4:5], v[6:7], 0, s[68:69]
	s_mov_b32 m0, s88
	s_addc_u32 s9, s41, 0
	global_load_lds_dwordx4 v[4:5], off
	s_add_i32 m0, s83, 0x1c000
	v_lshl_add_u64 v[4:5], s[8:9], 0, v[2:3]
	global_load_lds_dwordx4 v[4:5], off
	v_lshl_add_u64 v[4:5], s[8:9], 0, v[218:219]
	s_add_i32 m0, s83, 0x1e000
	s_cmpk_lt_u32 s6, 0x100
	global_load_lds_dwordx4 v[4:5], off
	s_cselect_b64 s[52:53], -1, 0
	v_cmp_lt_i32_e32 vcc, v236, v237
	s_lshl_b32 s6, s10, 2
	s_add_i32 s89, s6, 0
	v_cndmask_b32_e32 v4, v234, v236, vcc
	v_cmp_lt_i32_e32 vcc, v252, v237
	v_lshlrev_b32_e32 v243, 2, v4
	s_add_i32 s89, s89, 0x20400
	v_cndmask_b32_e32 v4, v234, v252, vcc
	s_lshl_b32 s5, s5, 10
	s_movk_i32 s8, 0x1600
	v_lshlrev_b32_e32 v244, 2, v4
	s_add_i32 s90, s89, s5
	v_lshrrev_b32_e32 v5, 1, v16
	v_mul_lo_u32 v4, v18, s8
	s_mov_b32 s5, 0x16000
	s_lshl_b32 s91, s7, 5
	v_mad_u64_u32 v[4:5], s[6:7], v5, s5, v[4:5]
	v_or_b32_e32 v4, v4, v17
	v_add_lshl_u32 v4, v4, v19, 1
	v_mov_b32_e32 v5, v3
	s_mov_b64 s[10:11], 0x160080
	v_lshl_add_u64 v[220:221], v[4:5], 0, s[10:11]
	v_lshrrev_b32_e32 v5, 1, v12
	v_mul_lo_u32 v4, v14, s8
	s_or_b32 s92, s4, 32
	v_mad_u64_u32 v[4:5], s[6:7], v5, s5, v[4:5]
	s_waitcnt vmcnt(8)
	s_barrier
	s_waitcnt vmcnt(6)
	s_cmp_eq_u64 s[26:27], 0
	v_or_b32_e32 v4, v4, v13
	s_cselect_b64 s[54:55], -1, 0
	s_cmp_lg_u64 s[26:27], 0
	v_add_lshl_u32 v4, v4, v15, 1
	v_mov_b32_e32 v5, v3
	s_cselect_b64 s[56:57], -1, 0
	v_lshl_add_u64 v[222:223], v[4:5], 0, s[10:11]
	s_mov_b64 s[42:43], -1
	v_add_u32_e32 v245, 0, v22
	s_barrier
	s_branch .LBB0_1129
